# v52: v37 + attention unit mapping puts the two workgroups of a (batch, head) on the same XCD (head = u & 7, half = bit 3) so the second K/V stream hits that XCD's L2
# baseline (speedup 1.0000x reference)
; __device__ __forceinline__ void attn_phase(LAS unsigned char* lds, const bf16_t* Q, const bf16_t* KN, const bf16_t* P, const bf16_t* VT, bf16_t* CAT, int bid, int G, const int tid) {
;     ...
;         const int rnd = u >> 8, c = u & 255, bh = c >> 1, half = c & 1;
;         const int qb = half ? (rnd == 0 ? 5 : rnd == 1 ? 2 : rnd == 2 ? 4 : 3) : (rnd == 0 ? 7 : rnd == 1 ? 0 : rnd == 2 ? 6 : 1);
.LBB0_139:
	s_ashr_i32 s26, s17, 8
	s_bfe_u32 s34, s17, 0x10003
	s_cmpk_lt_u32 s17, 0x100
	s_cselect_b64 s[4:5], -1, 0
	s_cmp_eq_u32 s26, 1
	s_cselect_b64 s[20:21], -1, 0
	s_cmp_eq_u32 s26, 2
	s_cselect_b64 s[30:31], -1, 0
	s_cmp_eq_u32 s34, 0
	s_mov_b64 s[34:35], -1
	s_cbranch_scc1 .LBB0_141
	s_and_b64 s[34:35], s[30:31], exec
	s_cselect_b32 s26, 4, 3
	s_and_b64 s[34:35], s[20:21], exec
	s_cselect_b32 s26, 2, s26
	s_and_b64 s[34:35], s[4:5], exec
	s_cselect_b32 s38, 5, s26
	s_mov_b64 s[34:35], 0

; __device__ __forceinline__ void attn_phase(LAS unsigned char* lds, const bf16_t* Q, const bf16_t* KN, const bf16_t* P, const bf16_t* VT, bf16_t* CAT, int bid, int G, const int tid) {
;     ...
;         const int b = bh >> 3, hh = bh & 7, nt = 4 * (qb + 1);
;         const size_t tok0 = (size_t)b * SEQ;
;         const int qlo = qb * 256 + 32 * w;
;         bf16x8 qf[2][6];
; #pragma unroll
;         for (int qi = 0; qi < 2; ++qi)
; #pragma unroll
;             for (int ch = 0; ch < 6; ++ch) qf[qi][ch] = *(const bf16x8*)(Q + (tok0 + qlo + 16 * qi + fr) * QW + hh * 192 + ch * 32 + fq * 8);
;         f32x4 o[8][2];
; #pragma unroll
;         for (int d = 0; d < 8; ++d) { o[d][0] = (f32x4){0.f, 0.f, 0.f, 0.f}; o[d][1] = (f32x4){0.f, 0.f, 0.f, 0.f}; }
;         float mrow[2] = {-INFINITY, -INFINITY}, lrow[2] = {0.f, 0.f};
;         const int kkey0 = tid >> 4, kc16 = tid & 15;
;         const int pkey = tid >> 3, pc8 = tid & 7;
;         const int vd0 = tid >> 3, vc8 = tid & 7;
;         const bf16_t* gk = KN + (tok0 + kkey0) * 1024 + hh * 128 + kc16 * 8;
;         const bf16_t* gp = P + (tok0 + pkey) * P_LD + OFF_KPE + pc8 * 8;
;         const bf16_t* gv = VT + (size_t)(hh * 128 + vd0) * M + tok0 + vc8 * 8;
;         const int lk = (kkey0 * KS + kc16 * 8) * 2, lp = (pkey * KS + 128 + pc8 * 8) * 2, lv = KBYTES + (vd0 * VS + vc8 * 8) * 2;
;         u32x4 rk0, rk1, rp, rv0, rv1;
;         rk0 = *(const u32x4*)(gk); rk1 = *(const u32x4*)(gk + 32 * 1024); rp = *(const u32x4*)(gp);
;         rv0 = *(const u32x4*)(gv); rv1 = *(const u32x4*)(gv + (size_t)64 * M);
.LBB0_143:
	s_bfe_u32 s4, s13, 0x4000b
	s_and_b32 s30, s17, 7
	v_mad_u64_u32 v[164:165], s[4:5], s4, v232, v[194:195]
	s_lshl_b32 s20, s30, 7
	s_lshl_b32 s4, s13, 11
	v_add_u32_e32 v0, s20, v188
	s_and_b32 s5, s4, 0x3c00000
	s_lshl_b32 s4, s30, 8
	v_ashrrev_i32_e32 v1, 31, v0
	s_or_b32 s26, s4, s5
	v_lshlrev_b64 v[0:1], 16, v[0:1]
	s_lshl_b32 s5, s13, 1
	v_or_b32_e32 v2, v192, v0
	s_and_b32 s5, s5, 0xf000
	s_lshl_b32 s34, s38, 8
	v_or_b32_e32 v168, s5, v2
	s_lshl_b32 s5, s17, 7
	s_add_i32 s21, s34, s3
	v_lshl_add_u64 v[166:167], s[26:27], 0, v[196:197]
	s_and_b32 s26, s5, 0x7800
	s_ashr_i32 s5, s21, 31
	s_add_u32 s31, s21, s26
	v_or_b32_e32 v200, s31, v178
	s_mulk_i32 s30, 0x180
	s_mov_b32 s31, s27
	v_lshl_add_u64 v[2:3], v[184:185], 0, s[30:31]
	s_addc_u32 s5, s5, 0
	v_mad_u64_u32 v[2:3], s[30:31], v200, s9, v[2:3]
	v_mad_i32_i24 v3, s5, v233, v3
	s_mov_b64 s[30:31], 0xc000
	flat_load_dwordx4 v[104:107], v[2:3]
	flat_load_dwordx4 v[92:95], v[2:3] offset:64
	flat_load_dwordx4 v[88:91], v[2:3] offset:128
	flat_load_dwordx4 v[76:79], v[2:3] offset:192
	flat_load_dwordx4 v[72:75], v[2:3] offset:256
	flat_load_dwordx4 v[64:67], v[2:3] offset:320
	v_lshl_add_u64 v[4:5], v[2:3], 0, s[30:31]
	v_add_co_u32_e32 v2, vcc, s73, v2
	v_readlane_b32 s38, v255, 4
	s_nop 0
	v_addc_co_u32_e32 v3, vcc, 0, v3, vcc
	flat_load_dwordx4 v[108:111], v[2:3]
	flat_load_dwordx4 v[100:103], v[4:5] offset:64
	flat_load_dwordx4 v[96:99], v[4:5] offset:128
	flat_load_dwordx4 v[84:87], v[4:5] offset:192
	flat_load_dwordx4 v[80:83], v[4:5] offset:256
	flat_load_dwordx4 v[68:71], v[4:5] offset:320
	v_lshl_add_u64 v[2:3], s[26:27], 0, v[186:187]
	v_lshlrev_b64 v[2:3], 11, v[2:3]
	v_readlane_b32 s39, v255, 5
	v_mov_b32_e32 v201, s5
	s_mov_b32 s5, s27
	v_lshl_add_u64 v[2:3], s[38:39], 0, v[2:3]
	v_lshl_add_u64 v[2:3], v[2:3], 0, s[4:5]
	v_lshl_add_u64 v[2:3], v[2:3], 0, v[176:177]
	v_add_u32_e32 v6, s26, v188
	v_mov_b64_e32 v[4:5], s[10:11]
	v_mad_i64_i32 v[4:5], s[4:5], v6, s48, v[4:5]
	v_mov_b32_e32 v199, v177
	flat_load_dwordx4 v[112:115], v[2:3]
	v_add_co_u32_e32 v2, vcc, 0x10000, v2
	v_mov_b32_e32 v169, v1
	v_lshl_add_u64 v[4:5], v[4:5], 0, v[198:199]
	v_lshl_add_u64 v[0:1], s[54:55], 0, v[0:1]
	s_lshl_b32 s26, s26, 1
	v_addc_co_u32_e32 v3, vcc, 0, v3, vcc
	v_lshl_add_u64 v[0:1], v[0:1], 0, s[26:27]
	flat_load_dwordx4 v[116:119], v[2:3]
	v_add_co_u32_e32 v2, vcc, 0x1000, v4
	v_lshl_add_u64 v[0:1], v[0:1], 0, v[198:199]
	s_nop 0
	v_addc_co_u32_e32 v3, vcc, 0, v5, vcc
	flat_load_dwordx4 v[120:123], v[2:3] offset:2176
	flat_load_dwordx4 v[124:127], v[0:1]
	v_add_co_u32_e32 v0, vcc, 0x400000, v0
	v_mov_b32_e32 v28, v177
	s_nop 0
	v_addc_co_u32_e32 v1, vcc, 0, v1, vcc
	flat_load_dwordx4 v[128:131], v[0:1]
	v_mov_b32_e32 v29, v177
	v_mov_b32_e32 v30, v177
	v_mov_b32_e32 v31, v177
	v_or_b32_e32 v244, s21, v178
	v_mov_b64_e32 v[62:63], v[30:31]
	v_mov_b64_e32 v[24:25], v[28:29]
	v_mov_b64_e32 v[58:59], v[30:31]
	v_mov_b64_e32 v[20:21], v[28:29]
	v_mov_b64_e32 v[50:51], v[30:31]
	v_mov_b64_e32 v[16:17], v[28:29]
	v_mov_b64_e32 v[54:55], v[30:31]
	v_mov_b64_e32 v[12:13], v[28:29]
	v_mov_b64_e32 v[46:47], v[30:31]
	v_mov_b64_e32 v[8:9], v[28:29]
	v_mov_b64_e32 v[42:43], v[30:31]
	v_mov_b64_e32 v[4:5], v[28:29]
	v_mov_b64_e32 v[38:39], v[30:31]
	v_mov_b64_e32 v[0:1], v[28:29]
	v_mov_b64_e32 v[34:35], v[30:31]
	s_mov_b32 s30, 0
	s_or_b32 s26, s21, 31
	v_or_b32_e32 v199, 16, v244
	s_or_b32 s31, s34, 0xc0
	v_mov_b32_e32 v202, v177
	v_mov_b32_e32 v203, v177
	v_mov_b32_e32 v206, 0xff800000
	v_mov_b64_e32 v[60:61], v[28:29]
	v_mov_b64_e32 v[26:27], v[30:31]
	v_mov_b64_e32 v[56:57], v[28:29]
	v_mov_b64_e32 v[22:23], v[30:31]
	v_mov_b64_e32 v[48:49], v[28:29]
	v_mov_b64_e32 v[18:19], v[30:31]
	v_mov_b64_e32 v[52:53], v[28:29]
	v_mov_b64_e32 v[14:15], v[30:31]
	v_mov_b64_e32 v[44:45], v[28:29]
	v_mov_b64_e32 v[10:11], v[30:31]
	v_mov_b64_e32 v[40:41], v[28:29]
	v_mov_b64_e32 v[6:7], v[30:31]
	v_mov_b64_e32 v[36:37], v[28:29]
	v_mov_b64_e32 v[2:3], v[30:31]
	v_mov_b64_e32 v[32:33], v[28:29]
	v_mov_b32_e32 v207, 0xff800000
	s_mov_b32 s34, 0
	s_branch .LBB0_146
